# v69 + NSA selection: union of the per-query selection masks reduced with DPP row ops + one readlane instead of five dependent ds_bpermute round trips
# baseline (speedup 1.0000x reference)
; DI void phase_attn_nsa(const Params& P, bf16_t* og, unsigned char* smem, int L, int G) {
;     ...
;     const unsigned sel = selL[r];
;     unsigned selU = sel;
;     selU |= (unsigned)__shfl_xor((int)selU, 1, 64); selU |= (unsigned)__shfl_xor((int)selU, 2, 64); selU |= (unsigned)__shfl_xor((int)selU, 4, 64);
;     selU |= (unsigned)__shfl_xor((int)selU, 8, 64); selU |= (unsigned)__shfl_xor((int)selU, 16, 64);
;     selU = (unsigned)__builtin_amdgcn_readfirstlane((int)selU);
;     tot_store(totL, tid, o0, o1, g0);
;     {
;       const bf16_t* kb = big + NS_KS + (size_t)b * SEQ * 256 + g * 64;
;       const bf16_t* vb = big + NS_VST + (size_t)((b * 4 + g) * 64) * SEQ;
;       float m = NEGF, l = 0.f; o_zero(o0, o1);
;       const int jhi = (t0 + 31) >> 6;
;       KVR R; kv64_fetch(R, kb, 256, vb, SEQ, 0, true, tid);
;       __syncthreads();
;       kv64_store(R, sK, sVt, tid);
;       if (0 < jhi) kv64_fetch(R, kb, 256, vb, SEQ, 64, true, tid);
.LBB0_1340:
	s_and_b64 s[0:1], s[16:17], s[0:1]
	s_or_b64 s[0:1], s[14:15], s[0:1]
	v_cndmask_b32_e64 v0, 0, 1, s[0:1]
	v_cmp_ne_u32_e32 vcc, 0, v0
	s_and_saveexec_b64 s[0:1], s[8:9]
	s_nop 0
	v_lshrrev_b64 v[36:37], v45, vcc
	ds_write_b32 v46, v36 offset:36960
	s_or_b64 exec, exec, s[0:1]
	s_waitcnt lgkmcnt(0)
	s_barrier
	ds_read_b32 v183, v39 offset:36864
	v_readlane_b32 s0, v246, 44
	v_lshlrev_b64 v[36:37], 20, v[114:115]
	v_readlane_b32 s1, v246, 45
	s_waitcnt lgkmcnt(0)
	v_lshlrev_b32_e32 v0, 7, v119
	v_lshl_add_u64 v[36:37], s[0:1], 0, v[36:37]
	v_readlane_b32 s0, v246, 46
	v_lshl_add_u64 v[36:37], v[36:37], 0, v[0:1]
	v_lshlrev_b64 v[38:39], 12, v[116:117]
	v_readlane_b32 s1, v246, 47
	v_lshlrev_b32_e32 v0, 9, v169
	v_mov_b32_e32 v141, v1
	v_lshl_add_u64 v[44:45], s[0:1], 0, v[38:39]
	v_lshl_add_u64 v[38:39], v[36:37], 0, v[0:1]
	v_lshlrev_b32_e32 v0, 9, v174
	v_lshl_add_u64 v[46:47], v[36:37], 0, v[0:1]
	v_lshl_add_u64 v[38:39], v[38:39], 0, v[140:141]
	v_lshl_add_u64 v[46:47], v[46:47], 0, v[140:141]
	v_lshlrev_b32_e32 v0, 12, v169
	global_load_dwordx4 v[90:93], v[38:39], off
	global_load_dwordx4 v[94:97], v[46:47], off
	v_lshl_add_u64 v[46:47], v[44:45], 0, v[0:1]
	v_lshlrev_b32_e32 v0, 12, v174
	v_lshl_add_u64 v[44:45], v[44:45], 0, v[0:1]
	v_lshl_add_u64 v[146:147], v[46:47], 0, v[140:141]
	v_lshl_add_u64 v[148:149], v[44:45], 0, v[140:141]
	global_load_dwordx4 v[98:101], v[146:147], off
	global_load_dwordx4 v[102:105], v[148:149], off
	v_mov_b32_e32 v0, v183
	s_nop 1
	v_or_b32_dpp v0, v0, v0 quad_perm:[1,0,3,2] row_mask:0xf bank_mask:0xf
	s_nop 1
	v_or_b32_dpp v0, v0, v0 quad_perm:[2,3,0,1] row_mask:0xf bank_mask:0xf
	s_nop 1
	v_or_b32_dpp v0, v0, v0 row_half_mirror row_mask:0xf bank_mask:0xf
	s_nop 1
	v_or_b32_dpp v0, v0, v0 row_mirror row_mask:0xf bank_mask:0xf
	s_nop 1
	v_readlane_b32 s98, v0, 16
	s_nop 0
	v_or_b32_e32 v0, s98, v0
	v_lshl_add_u32 v180, v42, 4, v153
	v_add_u32_e32 v181, 0x9200, v180
	s_cmp_lt_u32 s44, 2
	s_mov_b32 s8, 0xff61b1e6
	v_pk_mul_f32 v[2:3], v[34:35], v[2:3] op_sel_hi:[0,1]
	v_pk_mul_f32 v[4:5], v[34:35], v[4:5] op_sel_hi:[0,1]
	v_pk_mul_f32 v[18:19], v[34:35], v[18:19] op_sel_hi:[0,1]
	v_pk_mul_f32 v[20:21], v[34:35], v[20:21] op_sel_hi:[0,1]
	ds_write_b128 v180, v[2:5] offset:37376
	ds_write_b128 v180, v[18:21] offset:53760
	v_pk_mul_f32 v[2:3], v[34:35], v[6:7] op_sel_hi:[0,1]
	v_pk_mul_f32 v[4:5], v[34:35], v[8:9] op_sel_hi:[0,1]
	v_pk_mul_f32 v[6:7], v[34:35], v[22:23] op_sel_hi:[0,1]
	v_pk_mul_f32 v[8:9], v[34:35], v[24:25] op_sel_hi:[0,1]
	ds_write_b128 v180, v[2:5] offset:41472
	ds_write_b128 v180, v[6:9] offset:57856
	v_pk_mul_f32 v[2:3], v[34:35], v[10:11] op_sel_hi:[0,1]
	v_pk_mul_f32 v[4:5], v[34:35], v[12:13] op_sel_hi:[0,1]
	v_readfirstlane_b32 s2, v0
	v_pk_mul_f32 v[6:7], v[34:35], v[26:27] op_sel_hi:[0,1]
	v_pk_mul_f32 v[8:9], v[34:35], v[28:29] op_sel_hi:[0,1]
	ds_write_b128 v180, v[2:5] offset:45568
	ds_write_b128 v180, v[6:9] offset:61952
	v_pk_mul_f32 v[2:3], v[34:35], v[14:15] op_sel_hi:[0,1]
	v_pk_mul_f32 v[4:5], v[34:35], v[16:17] op_sel_hi:[0,1]
	v_pk_mul_f32 v[6:7], v[34:35], v[30:31] op_sel_hi:[0,1]
	v_pk_mul_f32 v[8:9], v[34:35], v[32:33] op_sel_hi:[0,1]
	ds_write_b128 v180, v[2:5] offset:49664
	ds_write_b128 v181, v[6:9] offset:28672
	s_waitcnt lgkmcnt(0)
	s_barrier
	s_waitcnt vmcnt(3)
	ds_write_b128 v170, v[90:93]
	s_waitcnt vmcnt(2)
	ds_write_b128 v170, v[94:97] offset:4608
	s_waitcnt vmcnt(1)
	ds_write_b128 v170, v[98:101] offset:9216
	s_waitcnt vmcnt(0)
	ds_write_b128 v170, v[102:105] offset:13824
	s_cbranch_scc1 .LBB0_1344
	v_add_co_u32_e32 v2, vcc, 0x8000, v38
	s_nop 1
	v_addc_co_u32_e32 v3, vcc, 0, v39, vcc
	v_add_co_u32_e32 v4, vcc, 0xc000, v38
	s_nop 1
	v_addc_co_u32_e32 v5, vcc, 0, v39, vcc
	global_load_dwordx4 v[90:93], v[2:3], off
	global_load_dwordx4 v[94:97], v[4:5], off
	global_load_dwordx4 v[98:101], v[146:147], off offset:128
	global_load_dwordx4 v[102:105], v[148:149], off offset:128
